# idle-slot filling part 3: phase 0 skipped for layers 1..3 (W2A in phase-1 slot, small matrices + LV in phase-10 slot)
# baseline (speedup 1.0000x reference)
; __global__ void __launch_bounds__(512) mega(Params P) {
;     ...
;     for (int ph = 0; ph < NL * 12 + 1; ++ph) {
;         const int l = ph / 12, kph = ph - l * 12;
;         if (kph == 7 && ph != NL * 12) continue;
.LBB0_8:
	s_mul_i32 s1, s0, 0xab
	s_bfe_u32 s1, s1, 0x5000b
	s_mul_i32 s96, s1, -12
	s_add_i32 s96, s96, s0
	s_cmp_eq_u32 s96, 7
	s_cselect_b64 s[4:5], -1, 0
	s_cmp_eq_u32 s96, 0
	s_cselect_b64 s[6:7], -1, 0
	s_cmp_lg_u32 s0, 0
	s_cselect_b64 s[8:9], -1, 0
	s_and_b64 s[6:7], s[6:7], s[8:9]
	s_or_b64 s[4:5], s[4:5], s[6:7]
	s_cmp_lg_u32 s0, 48
	s_cselect_b64 s[6:7], -1, 0
	s_and_b64 s[4:5], s[6:7], s[4:5]
	s_movk_i32 s58, 0x410
	s_and_b64 vcc, exec, s[4:5]
	s_mov_b32 s8, 4
	s_cbranch_vccz .LBB0_9
	s_getpc_b64 s[98:99]

; #define PH_BEGIN const int zi = opaque0(); unsigned char* ws = P.ws + zi; float* const OUT = P.out + zi; (void)OUT; const int tid = opqv((int)threadIdx.x); const int bid = opqs((int)blockIdx.x); const int G = opqs((int)gridDim.x); (void)tid; (void)bid; (void)G; unsigned char* WB = ws + WS_WB; float* SS = (float*)(ws + WS_SS); (void)WB; (void)SS; (void)zi;
; __global__ void __launch_bounds__(512) mega(Params P) {
;     ...
;         for (int rep = 0; rep < REPG; ++rep) {
;         { PH_BEGIN
;             pg8::Gemm g{XB_, (const bf16_t*)(WB + WB_W2A), T, 2 * FF, D, D, D, 0, 0}; pg8::StaticOrder S; S.init(T, 2 * FF, G, bid, 1);
;             EpiFFNa E{(bf16_t*)U_, SS + (size_t)2 * T * 16}; pg8::gemm_phase(lds, g, S, E, tid);
;         }
.LBB0_66:
	s_barrier
	s_cmpk_lt_u32 s2, 0x80
	s_cbranch_scc1 .Lp10_noextra
	s_mov_b32 s100, 2
	s_movk_i32 s101, 0x80
	s_mul_i32 s1, s0, 0xab
	s_bfe_u32 s1, s1, 0x5000b
	s_and_b32 s16, s1, 0xffff
	s_mul_i32 s18, s16, 0x2c0000
	s_mov_b32 s28, 0xc000
	s_mov_b32 s29, 0xe000
	s_mov_b32 s72, 0xd000
	s_mov_b32 s73, 0x9000
	s_movk_i32 s74, 0x7000
	s_sub_i32 s2, s2, 0x80
	s_movk_i32 s3, 0x80
	s_branch .Lp10_tramp_f

; #define PH_BEGIN const int zi = opaque0(); unsigned char* ws = P.ws + zi; float* const OUT = P.out + zi; (void)OUT; const int tid = opqv((int)threadIdx.x); const int bid = opqs((int)blockIdx.x); const int G = opqs((int)gridDim.x); (void)tid; (void)bid; (void)G; unsigned char* WB = ws + WS_WB; float* SS = (float*)(ws + WS_SS); (void)WB; (void)SS; (void)zi;
; __global__ void __launch_bounds__(512) mega(Params P) {
;     ...
;             { PH_BEGIN convT_w<1>(INP(30) + (size_t)l * D * 2 * FF, 2 * FF, 0, INP(29) + (size_t)l * D, (bf16_t*)(WB + WB_W2A), D, D, 2 * FF, bid * 8 + (tid >> 6), G * 8, tid & 63, 4800); }
;     ...
;         for (int rep = 0; rep < REPG; ++rep) {
;         { PH_BEGIN
;             pg8::Gemm g{XB_, (const bf16_t*)(WB + WB_W1A), T, 2 * FF, D, D, D, 0, 0}; pg8::StaticOrder S; S.init(T, 2 * FF, G, bid, 1);
;             EpiFFNa E{(bf16_t*)U_, SS + (size_t)0 * T * 16}; pg8::gemm_phase(lds, g, S, E, tid);
;         }
;         if ((int)blockIdx.x >= (int)gridDim.x - 16) { PH_BEGIN
;             pg8::Gemm g2{(const bf16_t*)(ws + WS_MEMN), (const bf16_t*)(WB + WB_WKV), 1024, D, D, D, D, 0, 0}; pg8::StaticOrder S2; S2.init(1024, D, 16, bid - (G - 16), 1);
;             EpiKV E2{KB_, VT_, (const float*)(ws + WS_MISC)}; pg8::gemm_phase(lds, g2, S2, E2, tid);
;         }
;         }
.LBB0_681:
	s_cmpk_lt_u32 s2, 0x80
	s_cbranch_scc1 .Lp1_noextra
	s_cmpk_gt_u32 s2, 0xef
	s_cbranch_scc1 .Lp1_noextra
	s_mul_i32 s1, s0, 0xab
	s_bfe_u32 s1, s1, 0x5000b
	s_and_b32 s16, s1, 0xffff
	s_lshl_b32 s19, s16, 10
	s_mov_b32 s28, 0xc000
	s_mov_b32 s29, 0xe000
	s_mov_b32 s72, 0xd000
	s_mov_b32 s73, 0x9000
	s_movk_i32 s74, 0x7000
	s_sub_i32 s2, s2, 0x80
	s_movk_i32 s3, 0x70
	s_mov_b32 s100, 1
	s_movk_i32 s101, 0x70
	s_mul_i32 s17, s16, 0x580000
	s_branch .Lp0_mov_entry
.Lp1_back:
	s_mov_b32 s100, 0
	s_and_b32 s2, s2, 0xffff
	s_add_i32 s2, s2, 0x80
	s_movk_i32 s3, 0x100

; #define PH_BEGIN const int zi = opaque0(); unsigned char* ws = P.ws + zi; float* const OUT = P.out + zi; (void)OUT; const int tid = opqv((int)threadIdx.x); const int bid = opqs((int)blockIdx.x); const int G = opqs((int)gridDim.x); (void)tid; (void)bid; (void)G; unsigned char* WB = ws + WS_WB; float* SS = (float*)(ws + WS_SS); (void)WB; (void)SS; (void)zi;
; __global__ void __launch_bounds__(512) mega(Params P) {
;     ...
;             { PH_BEGIN convT_w<1>(INP(3) + (size_t)l * D * 2 * FF, 2 * FF, 0, INP(2) + (size_t)l * D, (bf16_t*)(WB + WB_W1A), D, D, 2 * FF, bid * 8 + (tid >> 6), G * 8, tid & 63, 0); }
.LBB0_682:
	s_and_b64 vcc, exec, s[4:5]
	s_cbranch_vccz .LBB0_778
	s_cmp_lg_u32 s96, 0
	s_cbranch_scc1 .LBB0_778
	s_mov_b32 s100, 0
	s_movk_i32 s101, 0x100

; #define PH_BEGIN const int zi = opaque0(); unsigned char* ws = P.ws + zi; float* const OUT = P.out + zi; (void)OUT; const int tid = opqv((int)threadIdx.x); const int bid = opqs((int)blockIdx.x); const int G = opqs((int)gridDim.x); (void)tid; (void)bid; (void)G; unsigned char* WB = ws + WS_WB; float* SS = (float*)(ws + WS_SS); (void)WB; (void)SS; (void)zi;
; __global__ void __launch_bounds__(512) mega(Params P) {
;     ...
;             { PH_BEGIN convT_w<0>(INP(26) + (size_t)l * D * D, D, 0, INP(6) + (size_t)l * D, (bf16_t*)(WB + WB_WKV), D, D, D, bid * 8 + (tid >> 6), G * 8, tid & 63, 4544); }
.LBB0_720:
	s_or_b64 exec, exec, s[4:5]
	s_and_b32 s2, s2, 0xffff
	s_mov_b32 s3, s101
	s_cmp_eq_u32 s100, 1
	s_cbranch_scc0 .Lh720_done
	s_or_b32 s2, s2, 0x10000
	s_mov_b32 s3, 0x100000

; #define PH_BEGIN const int zi = opaque0(); unsigned char* ws = P.ws + zi; float* const OUT = P.out + zi; (void)OUT; const int tid = opqv((int)threadIdx.x); const int bid = opqs((int)blockIdx.x); const int G = opqs((int)gridDim.x); (void)tid; (void)bid; (void)G; unsigned char* WB = ws + WS_WB; float* SS = (float*)(ws + WS_SS); (void)WB; (void)SS; (void)zi;
; template <int MAP>
; __device__ __forceinline__ void convT_w(const float* src, int ld, int coff, const float* g, bf16_t* dst, int K, int Kd, int Nd, int wslot, int nslots, int lane, int tile_base) {
;     const int nkt = K >> 4, nnt = (Nd + 255) >> 8, ntile = nkt * nnt;
;     for (int t = ((wslot - tile_base) % nslots + nslots) % nslots; t < ntile; t += nslots) {
;         const int kt = t % nkt, ntl = t / nkt, k0 = kt * 16, n = ntl * 256 + lane * 4; const int c = (n < Nd) ? colmap<MAP>(n) : -1;
;         const float* sp = src + (size_t)k0 * ld + coff + (c >= 0 ? c : 0);
; __global__ void __launch_bounds__(512) mega(Params P) {
;     ...
;             { PH_BEGIN convT_w<1>(INP(30) + (size_t)l * D * 2 * FF, 2 * FF, 0, INP(29) + (size_t)l * D, (bf16_t*)(WB + WB_W2A), D, D, 2 * FF, bid * 8 + (tid >> 6), G * 8, tid & 63, 4800); }
.LBB0_727:
	s_or_b64 exec, exec, s[4:5]
	s_or_b32 s2, s2, 0x10000
	s_mov_b32 s3, 0x100000
	s_cmp_eq_u32 s100, 1
	s_cbranch_scc0 .Lh727_done
	s_and_b32 s2, s2, 0xffff
	s_mov_b32 s3, s101
.Lh727_done:
	s_mov_b32 s4, s63
	v_mov_b32_e32 v0, v232
	s_mov_b32 s5, s2
	s_mov_b32 s6, s3
	s_lshl_b32 s20, s6, 3
	s_abs_i32 s6, s20
	s_waitcnt vmcnt(0)
	v_cvt_f32_u32_e32 v2, s6
	v_ashrrev_i32_e32 v3, 6, v0
	v_lshl_add_u32 v3, s5, 3, v3
	v_add_u32_e32 v3, 0xffffed40, v3
	v_rcp_iflag_f32_e32 v2, v2
	v_sub_u32_e32 v5, 0, v3
	s_sub_i32 s5, 0, s6
	v_ashrrev_i32_e32 v4, 31, v3
	v_mul_f32_e32 v2, 0x4f7ffffe, v2
	v_cvt_u32_f32_e32 v2, v2
	v_max_i32_e32 v3, v3, v5
	v_mul_lo_u32 v5, s5, v2
	v_mul_hi_u32 v5, v2, v5
	v_add_u32_e32 v2, v2, v5
	v_mul_hi_u32 v5, v3, v2
	v_mul_lo_u32 v5, v5, s6
	v_sub_u32_e32 v3, v3, v5
	v_subrev_u32_e32 v5, s6, v3
	v_cmp_le_u32_e32 vcc, s6, v3
	s_movk_i32 s5, 0x580
	s_nop 0
	v_cndmask_b32_e32 v3, v3, v5, vcc
	v_subrev_u32_e32 v5, s6, v3
	v_cmp_le_u32_e32 vcc, s6, v3
	s_nop 1
	v_cndmask_b32_e32 v3, v3, v5, vcc
	v_xor_b32_e32 v3, v3, v4
	v_sub_u32_e32 v3, v3, v4
	v_add_u32_e32 v3, s20, v3
	v_sub_u32_e32 v5, 0, v3
	v_ashrrev_i32_e32 v4, 31, v3
	v_max_i32_e32 v3, v3, v5
	v_mul_hi_u32 v2, v3, v2
	v_mul_lo_u32 v2, v2, s6
	v_sub_u32_e32 v2, v3, v2
	v_subrev_u32_e32 v3, s6, v2
	v_cmp_le_u32_e32 vcc, s6, v2
	s_nop 1
	v_cndmask_b32_e32 v2, v2, v3, vcc
	v_subrev_u32_e32 v3, s6, v2
	v_cmp_le_u32_e32 vcc, s6, v2
	s_nop 1
	v_cndmask_b32_e32 v2, v2, v3, vcc
	v_xor_b32_e32 v2, v2, v4
	v_sub_u32_e32 v20, v2, v4
	v_cmp_gt_i32_e32 vcc, s5, v20
	s_and_saveexec_b64 s[6:7], vcc
	s_cbranch_execz .LBB0_733
	v_readlane_b32 s36, v253, 39
	s_lshl_b32 s5, s17, 2
	v_readlane_b32 s48, v253, 51
	v_readlane_b32 s49, v253, 52
	s_add_u32 s8, s48, s5
	v_readlane_b32 s46, v253, 49
	s_addc_u32 s9, s49, 0
	v_readlane_b32 s47, v253, 50
	s_add_u32 s10, s46, s19
	s_addc_u32 s11, s47, 0
	s_ashr_i32 s5, s4, 31
	s_add_u32 s12, s92, s4
	s_addc_u32 s13, s93, s5
	s_lshl_b64 s[4:5], s[4:5], 2
	s_add_u32 s8, s8, s4
	s_addc_u32 s9, s9, s5
	s_add_u32 s10, s10, s4
	s_addc_u32 s11, s11, s5
	v_and_b32_e32 v0, 63, v0
	s_add_u32 s12, s12, 0x2980000
	v_lshlrev_b32_e32 v21, 2, v0
	s_addc_u32 s13, s13, 0
	v_cmp_gt_u32_e64 s[4:5], 32, v0
	v_add_u32_e32 v22, 0xa80, v21
	v_lshlrev_b32_e32 v23, 4, v20
	s_lshl_b32 s17, s20, 4
	s_mov_b64 s[14:15], 0
	v_readlane_b32 s37, v253, 40
	v_readlane_b32 s38, v253, 41
	v_readlane_b32 s39, v253, 42
	v_readlane_b32 s40, v253, 43
	v_readlane_b32 s41, v253, 44
	v_readlane_b32 s42, v253, 45
	v_readlane_b32 s43, v253, 46
	v_readlane_b32 s44, v253, 47
	v_readlane_b32 s45, v253, 48
	v_readlane_b32 s50, v253, 53
	v_readlane_b32 s51, v253, 54
	s_branch .LBB0_731

; #define PH_BEGIN const int zi = opaque0(); unsigned char* ws = P.ws + zi; float* const OUT = P.out + zi; (void)OUT; const int tid = opqv((int)threadIdx.x); const int bid = opqs((int)blockIdx.x); const int G = opqs((int)gridDim.x); (void)tid; (void)bid; (void)G; unsigned char* WB = ws + WS_WB; float* SS = (float*)(ws + WS_SS); (void)WB; (void)SS; (void)zi;
; __global__ void __launch_bounds__(512) mega(Params P) {
;     ...
;             { PH_BEGIN convT_w<1>(INP(30) + (size_t)l * D * 2 * FF, 2 * FF, 0, INP(29) + (size_t)l * D, (bf16_t*)(WB + WB_W2A), D, D, 2 * FF, bid * 8 + (tid >> 6), G * 8, tid & 63, 4800); }
;             { PH_BEGIN convT_w<0>(INP(31) + (size_t)l * FF * D, D, 0, nullptr, (bf16_t*)(WB + WB_W2B), FF, FF, D, bid * 8 + (tid >> 6), G * 8, tid & 63, 6208); }
.LBB0_733:
	s_or_b64 exec, exec, s[6:7]
	s_cmp_eq_u32 s100, 1
	s_cbranch_scc1 .Lp1_back
	s_or_b32 s2, s2, 0x10000
	s_mov_b32 s3, 0x100000

; #define PH_BEGIN const int zi = opaque0(); unsigned char* ws = P.ws + zi; float* const OUT = P.out + zi; (void)OUT; const int tid = opqv((int)threadIdx.x); const int bid = opqs((int)blockIdx.x); const int G = opqs((int)gridDim.x); (void)tid; (void)bid; (void)G; unsigned char* WB = ws + WS_WB; float* SS = (float*)(ws + WS_SS); (void)WB; (void)SS; (void)zi;
; __global__ void __launch_bounds__(512) mega(Params P) {
;     ...
;             { PH_BEGIN convT_w<0>(INP(31) + (size_t)l * FF * D, D, 0, nullptr, (bf16_t*)(WB + WB_W2B), FF, FF, D, bid * 8 + (tid >> 6), G * 8, tid & 63, 6208); }
;             { PH_BEGIN convT_w<0>(INP(10) + (size_t)l * 64 * 512, 512, 0, nullptr, (bf16_t*)(WB + WB_LW2), 64, 64, 512, bid * 8 + (tid >> 6), G * 8, tid & 63, 6912); }
;             { PH_BEGIN convT_w<0>(INP(12) + (size_t)l * 64 * 512, 512, 0, nullptr, (bf16_t*)(WB + WB_LA2), 64, 64, 512, bid * 8 + (tid >> 6), G * 8, tid & 63, 6920); }
;             { PH_BEGIN convT_w<0>(INP(13) + (size_t)l * 128 * 512, 512, 0, nullptr, (bf16_t*)(WB + WB_LG2), 128, 128, 512, bid * 8 + (tid >> 6), G * 8, tid & 63, 6928); }
.LBB0_738:
	s_or_b64 exec, exec, s[4:5]
	s_cmp_eq_u32 s100, 2
	s_cbranch_scc0 .Lh738_off
	s_cmp_eq_u32 s1, 3
	s_cbranch_scc1 .Lp10_tramp_b
	s_add_i32 s1, s1, 1
	s_mov_b32 s100, 3
	s_branch .Lp10_w1a_entry
.Lh738_off:
	s_and_b32 s2, s2, 0xffff
	s_mov_b32 s3, s101
	s_mov_b32 s6, s63
	v_mov_b32_e32 v0, v232
	s_mov_b32 s4, s2
	s_mov_b32 s5, s3
	s_lshl_b32 s15, s5, 3
	s_abs_i32 s5, s15
	v_cvt_f32_u32_e32 v2, s5
	v_ashrrev_i32_e32 v3, 6, v0
	v_lshl_add_u32 v3, s4, 3, v3
	v_add_u32_e32 v3, 0xffffe500, v3
	v_rcp_iflag_f32_e32 v2, v2
	v_sub_u32_e32 v5, 0, v3
	s_sub_i32 s4, 0, s5
	v_ashrrev_i32_e32 v4, 31, v3
	v_mul_f32_e32 v2, 0x4f7ffffe, v2
	v_cvt_u32_f32_e32 v2, v2
	v_max_i32_e32 v3, v3, v5
	s_lshl_b32 s14, s16, 15
	v_mul_lo_u32 v5, s4, v2
	v_mul_hi_u32 v5, v2, v5
	v_add_u32_e32 v2, v2, v5
	v_mul_hi_u32 v5, v3, v2
	v_mul_lo_u32 v5, v5, s5
	v_sub_u32_e32 v3, v3, v5
	v_subrev_u32_e32 v5, s5, v3
	v_cmp_le_u32_e32 vcc, s5, v3
	s_nop 1
	v_cndmask_b32_e32 v3, v3, v5, vcc
	v_subrev_u32_e32 v5, s5, v3
	v_cmp_le_u32_e32 vcc, s5, v3
	s_nop 1
	v_cndmask_b32_e32 v3, v3, v5, vcc
	v_xor_b32_e32 v3, v3, v4
	v_sub_u32_e32 v3, v3, v4
	v_add_u32_e32 v3, s15, v3
	v_sub_u32_e32 v5, 0, v3
	v_ashrrev_i32_e32 v4, 31, v3
	v_max_i32_e32 v3, v3, v5
	v_mul_hi_u32 v2, v3, v2
	v_mul_lo_u32 v2, v2, s5
	v_sub_u32_e32 v2, v3, v2
	v_subrev_u32_e32 v3, s5, v2
	v_cmp_le_u32_e32 vcc, s5, v2
	s_nop 1
	v_cndmask_b32_e32 v2, v2, v3, vcc
	v_subrev_u32_e32 v3, s5, v2
	v_cmp_le_u32_e32 vcc, s5, v2
	s_nop 1
	v_cndmask_b32_e32 v2, v2, v3, vcc
	v_xor_b32_e32 v2, v2, v4
	v_sub_u32_e32 v4, v2, v4
	v_cmp_gt_i32_e32 vcc, 8, v4
	s_and_saveexec_b64 s[4:5], vcc
	s_cbranch_execz .LBB0_743
	v_readlane_b32 s36, v252, 8
	s_lshl_b32 s7, s14, 2
	v_readlane_b32 s40, v252, 12
	v_readlane_b32 s41, v252, 13
	s_add_u32 s8, s40, s7
	s_addc_u32 s9, s41, 0
	s_ashr_i32 s7, s6, 31
	s_add_u32 s10, s92, s6
	s_addc_u32 s11, s93, s7
	s_lshl_b64 s[6:7], s[6:7], 2
	s_add_u32 s6, s8, s6
	s_addc_u32 s7, s9, s7
	s_add_u32 s8, s10, 0x3a00000
	v_lshlrev_b32_e32 v0, 2, v0
	s_addc_u32 s9, s11, 0
	v_and_b32_e32 v5, 0xfc, v0
	v_lshlrev_b32_e32 v6, 4, v4
	s_lshl_b32 s17, s15, 4
	s_mov_b64 s[10:11], 0
	v_readlane_b32 s37, v252, 9
	v_readlane_b32 s38, v252, 10
	v_readlane_b32 s39, v252, 11
	v_readlane_b32 s42, v252, 14
	v_readlane_b32 s43, v252, 15
	v_readlane_b32 s44, v252, 16
	v_readlane_b32 s45, v252, 17
	v_readlane_b32 s46, v252, 18
	v_readlane_b32 s47, v252, 19
	v_readlane_b32 s48, v252, 20
	v_readlane_b32 s49, v252, 21
	v_readlane_b32 s50, v252, 22
	v_readlane_b32 s51, v252, 23
	s_branch .LBB0_741

; #define PH_BEGIN const int zi = opaque0(); unsigned char* ws = P.ws + zi; float* const OUT = P.out + zi; (void)OUT; const int tid = opqv((int)threadIdx.x); const int bid = opqs((int)blockIdx.x); const int G = opqs((int)gridDim.x); (void)tid; (void)bid; (void)G; unsigned char* WB = ws + WS_WB; float* SS = (float*)(ws + WS_SS); (void)WB; (void)SS; (void)zi;
; __global__ void __launch_bounds__(512) mega(Params P) {
;     ...
;             if (l > 0) {
;                 { PH_BEGIN convT_w<0>(INP(20) + (size_t)(l - 1) * 512 * 32, 32, 0, nullptr, (bf16_t*)(WB + WB_LV1), 512, 512, 32, bid * 8 + (tid >> 6), G * 8, tid & 63, 6944); }
;                 { PH_BEGIN convT_w<0>(INP(21) + (size_t)(l - 1) * 32 * 512, 512, 0, nullptr, (bf16_t*)(WB + WB_LV2), 32, 32, 512, bid * 8 + (tid >> 6), G * 8, tid & 63, 6976); }
.LBB0_753:
	s_or_b64 exec, exec, s[4:5]
	s_cmp_eq_u32 s100, 3
	s_cbranch_scc1 .Lp10_lv_entry
	s_cmp_gt_u32 s0, 11
	s_mov_b64 s[4:5], -1
	s_cbranch_scc0 .LBB0_765
.Lp10_lv_entry:
	s_mov_b32 s8, s63
	v_mov_b32_e32 v0, v232
	s_mov_b32 s6, s2
	s_mov_b32 s4, s3
	s_lshl_b32 s16, s4, 3
	s_abs_i32 s7, s16
	v_cvt_f32_u32_e32 v2, s7
	v_ashrrev_i32_e32 v3, 6, v0
	v_lshl_add_u32 v3, s6, 3, v3
	v_add_u32_e32 v3, 0xffffe4e0, v3
	v_rcp_iflag_f32_e32 v2, v2
	s_add_i32 s62, s1, -1
	v_sub_u32_e32 v5, 0, v3
	s_sub_i32 s1, 0, s7
	v_mul_f32_e32 v2, 0x4f7ffffe, v2
	v_cvt_u32_f32_e32 v2, v2
	v_ashrrev_i32_e32 v4, 31, v3
	v_max_i32_e32 v3, v3, v5
	s_lshl_b64 s[4:5], s[62:63], 16
	v_mul_lo_u32 v5, s1, v2
	v_mul_hi_u32 v5, v2, v5
	v_add_u32_e32 v2, v2, v5
	v_mul_hi_u32 v5, v3, v2
	v_mul_lo_u32 v5, v5, s7
	v_sub_u32_e32 v3, v3, v5
	v_subrev_u32_e32 v5, s7, v3
	v_cmp_le_u32_e32 vcc, s7, v3
	s_nop 1
	v_cndmask_b32_e32 v3, v3, v5, vcc
	v_subrev_u32_e32 v5, s7, v3
	v_cmp_le_u32_e32 vcc, s7, v3
	s_nop 1
	v_cndmask_b32_e32 v3, v3, v5, vcc
	v_xor_b32_e32 v3, v3, v4
	v_sub_u32_e32 v3, v3, v4
	v_add_u32_e32 v3, s16, v3
	v_sub_u32_e32 v5, 0, v3
	v_ashrrev_i32_e32 v4, 31, v3
	v_max_i32_e32 v3, v3, v5
	v_mul_hi_u32 v2, v3, v2
	v_mul_lo_u32 v2, v2, s7
	v_sub_u32_e32 v2, v3, v2
	v_subrev_u32_e32 v3, s7, v2
	v_cmp_le_u32_e32 vcc, s7, v2
	s_nop 1
	v_cndmask_b32_e32 v2, v2, v3, vcc
	v_subrev_u32_e32 v3, s7, v2
	v_cmp_le_u32_e32 vcc, s7, v2
	s_nop 1
	v_cndmask_b32_e32 v2, v2, v3, vcc
	v_xor_b32_e32 v2, v2, v4
	v_sub_u32_e32 v4, v2, v4
	v_cmp_gt_i32_e32 vcc, 32, v4
	s_and_saveexec_b64 s[6:7], vcc
	s_cbranch_execz .LBB0_759
	v_readlane_b32 s36, v252, 24
	v_readlane_b32 s44, v252, 32
	v_readlane_b32 s45, v252, 33
	s_add_u32 s1, s44, s4
	s_addc_u32 s10, s45, s5
	s_ashr_i32 s9, s8, 31
	s_add_u32 s11, s92, s8
	s_addc_u32 s12, s93, s9
	s_lshl_b64 s[8:9], s[8:9], 2
	s_add_u32 s8, s1, s8
	s_addc_u32 s9, s10, s9
	s_add_u32 s10, s11, 0x3a40000
	v_lshlrev_b32_e32 v0, 2, v0
	s_addc_u32 s11, s12, 0
	v_and_b32_e32 v5, 0xfc, v0
	v_lshlrev_b32_e32 v6, 4, v4
	s_lshl_b32 s1, s16, 4
	s_mov_b64 s[12:13], 0
	v_readlane_b32 s37, v252, 25
	v_readlane_b32 s38, v252, 26
	v_readlane_b32 s39, v252, 27
	v_readlane_b32 s40, v252, 28
	v_readlane_b32 s41, v252, 29
	v_readlane_b32 s42, v252, 30
	v_readlane_b32 s43, v252, 31
	v_readlane_b32 s46, v252, 34
	v_readlane_b32 s47, v252, 35
	v_readlane_b32 s48, v252, 36
	v_readlane_b32 s49, v252, 37
	v_readlane_b32 s50, v252, 38
	v_readlane_b32 s51, v252, 39
	s_branch .LBB0_757

; #define PH_BEGIN const int zi = opaque0(); unsigned char* ws = P.ws + zi; float* const OUT = P.out + zi; (void)OUT; const int tid = opqv((int)threadIdx.x); const int bid = opqs((int)blockIdx.x); const int G = opqs((int)gridDim.x); (void)tid; (void)bid; (void)G; unsigned char* WB = ws + WS_WB; float* SS = (float*)(ws + WS_SS); (void)WB; (void)SS; (void)zi;
; __global__ void __launch_bounds__(512) mega(Params P) {
;     ...
;                 { PH_BEGIN convT_w<0>(INP(21) + (size_t)(l - 1) * 32 * 512, 512, 0, nullptr, (bf16_t*)(WB + WB_LV2), 32, 32, 512, bid * 8 + (tid >> 6), G * 8, tid & 63, 6976); }
;             }
.LBB0_764:
	s_or_b64 exec, exec, s[6:7]
	s_cmp_eq_u32 s100, 3
	s_cbranch_scc1 .Lp10_tramp_b
	s_mov_b64 s[4:5], 0
